# v5 + FoX softmax VALU cleanup: row-max tree via v_max3 (53->16 instr, 3 copies), D subtraction via neg modifiers instead of v_xor
# speedup vs baseline: 1.0236x; 1.0006x over previous
.LBB0_548:
	s_and_b64 s[44:45], s[0:1], s[42:43]
	s_andn2_b64 vcc, exec, s[44:45]
	s_cbranch_vccnz .LBB0_552
	v_max3_f32 v2, v82, v98, v99
	v_max3_f32 v4, v83, v100, v84
	v_max3_f32 v2, v2, v101, v85
	v_max3_f32 v4, v4, v102, v86
	v_max3_f32 v2, v2, v103, v87
	v_max3_f32 v4, v4, v104, v88
	v_max3_f32 v2, v2, v105, v89
	v_max3_f32 v4, v4, v106, v90
	v_max3_f32 v2, v2, v107, v91
	v_max3_f32 v4, v4, v108, v92
	v_max3_f32 v2, v2, v109, v93
	v_max3_f32 v4, v4, v110, v94
	v_max3_f32 v2, v2, v111, v95
	v_max3_f32 v4, v4, v112, v96
	v_max3_f32 v2, v2, v113, v97
	v_max_f32_e32 v2, v2, v4
	v_mov_b32_e32 v4, v2
	s_nop 1
	v_permlane32_swap_b32 v4, v2
	s_nop 1
	s_nop 0
	v_max3_f32 v16, v203, v4, v2
	v_sub_f32_e32 v2, v203, v16
	v_exp_f32_e32 v2, v2
	s_nop 0
	v_cmp_eq_f32_e32 vcc, 1.0, v2
	s_cmp_eq_u64 vcc, exec
	s_cbranch_scc1 .LBB0_551
	v_pk_mul_f32 v[80:81], v[80:81], v[2:3] op_sel_hi:[1,0]
	v_pk_mul_f32 v[78:79], v[78:79], v[2:3] op_sel_hi:[1,0]
	v_pk_mul_f32 v[76:77], v[76:77], v[2:3] op_sel_hi:[1,0]
	v_pk_mul_f32 v[74:75], v[74:75], v[2:3] op_sel_hi:[1,0]
	v_pk_mul_f32 v[72:73], v[72:73], v[2:3] op_sel_hi:[1,0]
	v_pk_mul_f32 v[70:71], v[70:71], v[2:3] op_sel_hi:[1,0]
	v_pk_mul_f32 v[68:69], v[68:69], v[2:3] op_sel_hi:[1,0]
	v_pk_mul_f32 v[66:67], v[66:67], v[2:3] op_sel_hi:[1,0]
	v_pk_mul_f32 v[64:65], v[64:65], v[2:3] op_sel_hi:[1,0]
	v_pk_mul_f32 v[62:63], v[62:63], v[2:3] op_sel_hi:[1,0]
	v_pk_mul_f32 v[60:61], v[60:61], v[2:3] op_sel_hi:[1,0]
	v_pk_mul_f32 v[58:59], v[58:59], v[2:3] op_sel_hi:[1,0]
	v_pk_mul_f32 v[56:57], v[56:57], v[2:3] op_sel_hi:[1,0]
	v_pk_mul_f32 v[54:55], v[54:55], v[2:3] op_sel_hi:[1,0]
	v_pk_mul_f32 v[52:53], v[52:53], v[2:3] op_sel_hi:[1,0]
	v_pk_mul_f32 v[50:51], v[50:51], v[2:3] op_sel_hi:[1,0]
	v_pk_mul_f32 v[48:49], v[48:49], v[2:3] op_sel_hi:[1,0]
	v_pk_mul_f32 v[46:47], v[46:47], v[2:3] op_sel_hi:[1,0]
	v_pk_mul_f32 v[44:45], v[44:45], v[2:3] op_sel_hi:[1,0]
	v_pk_mul_f32 v[42:43], v[42:43], v[2:3] op_sel_hi:[1,0]
	v_pk_mul_f32 v[40:41], v[40:41], v[2:3] op_sel_hi:[1,0]
	v_pk_mul_f32 v[38:39], v[38:39], v[2:3] op_sel_hi:[1,0]
	v_pk_mul_f32 v[36:37], v[36:37], v[2:3] op_sel_hi:[1,0]
	v_pk_mul_f32 v[34:35], v[34:35], v[2:3] op_sel_hi:[1,0]
	v_pk_mul_f32 v[32:33], v[32:33], v[2:3] op_sel_hi:[1,0]
	v_pk_mul_f32 v[30:31], v[30:31], v[2:3] op_sel_hi:[1,0]
	v_pk_mul_f32 v[28:29], v[28:29], v[2:3] op_sel_hi:[1,0]
	v_pk_mul_f32 v[26:27], v[26:27], v[2:3] op_sel_hi:[1,0]
	v_pk_mul_f32 v[24:25], v[24:25], v[2:3] op_sel_hi:[1,0]
	v_pk_mul_f32 v[22:23], v[22:23], v[2:3] op_sel_hi:[1,0]
	v_pk_mul_f32 v[20:21], v[20:21], v[2:3] op_sel_hi:[1,0]
	v_pk_mul_f32 v[18:19], v[18:19], v[2:3] op_sel_hi:[1,0]

.LBB0_553:
	s_mul_i32 s35, s34, 0x4400
	v_add_u32_e32 v2, s35, v217
	ds_read_b128 v[4:7], v2 offset:8704
	ds_read_b128 v[8:11], v2
	ds_read_b128 v[12:15], v2 offset:32
	s_add_i32 s35, s50, 63
	s_cmp_le_i32 s35, s38
	s_waitcnt lgkmcnt(2)
	v_mfma_f32_32x32x16_bf16 v[98:113], v[4:7], v[114:117], 0
	ds_read_b128 v[4:7], v2 offset:8736
	s_waitcnt lgkmcnt(2)
	v_mfma_f32_32x32x16_bf16 v[82:97], v[8:11], v[114:117], 0
	s_waitcnt lgkmcnt(1)
	v_mfma_f32_32x32x16_bf16 v[82:97], v[12:15], v[118:121], v[82:97]
	s_waitcnt lgkmcnt(0)
	v_mfma_f32_32x32x16_bf16 v[98:113], v[4:7], v[118:121], v[98:113]
	ds_read_b128 v[4:7], v2 offset:64
	ds_read_b128 v[8:11], v2 offset:8768
	s_waitcnt vmcnt(5) lgkmcnt(1)
	v_mfma_f32_32x32x16_bf16 v[82:97], v[4:7], v[122:125], v[82:97]
	s_waitcnt lgkmcnt(0)
	v_mfma_f32_32x32x16_bf16 v[98:113], v[8:11], v[122:125], v[98:113]
	ds_read_b128 v[4:7], v2 offset:96
	ds_read_b128 v[8:11], v2 offset:8800
	s_waitcnt vmcnt(4) lgkmcnt(1)
	v_mfma_f32_32x32x16_bf16 v[82:97], v[4:7], v[126:129], v[82:97]
	s_waitcnt lgkmcnt(0)
	v_mfma_f32_32x32x16_bf16 v[98:113], v[8:11], v[126:129], v[98:113]
	ds_read_b128 v[4:7], v2 offset:128
	ds_read_b128 v[8:11], v2 offset:8832
	s_waitcnt vmcnt(3) lgkmcnt(1)
	v_mfma_f32_32x32x16_bf16 v[82:97], v[4:7], v[130:133], v[82:97]
	s_waitcnt lgkmcnt(0)
	v_mfma_f32_32x32x16_bf16 v[98:113], v[8:11], v[130:133], v[98:113]
	ds_read_b128 v[4:7], v2 offset:160
	ds_read_b128 v[8:11], v2 offset:8864
	s_waitcnt vmcnt(2) lgkmcnt(1)
	v_mfma_f32_32x32x16_bf16 v[82:97], v[4:7], v[134:137], v[82:97]
	s_waitcnt lgkmcnt(0)
	v_mfma_f32_32x32x16_bf16 v[98:113], v[8:11], v[134:137], v[98:113]
	ds_read_b128 v[4:7], v2 offset:192
	ds_read_b128 v[8:11], v2 offset:8896
	s_waitcnt vmcnt(1) lgkmcnt(1)
	v_mfma_f32_32x32x16_bf16 v[82:97], v[4:7], v[138:141], v[82:97]
	s_waitcnt lgkmcnt(0)
	v_mfma_f32_32x32x16_bf16 v[98:113], v[8:11], v[138:141], v[98:113]
	ds_read_b128 v[4:7], v2 offset:224
	ds_read_b128 v[8:11], v2 offset:8928
	s_waitcnt vmcnt(0) lgkmcnt(1)
	v_mfma_f32_32x32x16_bf16 v[82:97], v[4:7], v[142:145], v[82:97]
	s_waitcnt lgkmcnt(0)
	v_mfma_f32_32x32x16_bf16 v[98:113], v[8:11], v[142:145], v[98:113]
	ds_read_b128 v[4:7], v183 offset:128
	ds_read_b128 v[8:11], v183
	ds_read_b128 v[12:15], v183 offset:32
	ds_read_b128 v[220:223], v183 offset:160
	ds_read_b128 v[224:227], v183 offset:64
	ds_read_b128 v[228:231], v183 offset:192
	ds_read_b128 v[232:235], v183 offset:96
	ds_read_b128 v[236:239], v183 offset:224
	s_waitcnt lgkmcnt(6)
	s_nop 0
	v_pk_fma_f32 v[82:83], v[82:83], s[16:17], v[8:9] op_sel_hi:[1,0,1] neg_lo:[0,0,1] neg_hi:[0,0,1]
	v_pk_fma_f32 v[84:85], v[84:85], s[16:17], v[10:11] op_sel_hi:[1,0,1] neg_lo:[0,0,1] neg_hi:[0,0,1]
	s_waitcnt lgkmcnt(5)
	v_pk_fma_f32 v[86:87], v[86:87], s[16:17], v[12:13] op_sel_hi:[1,0,1] neg_lo:[0,0,1] neg_hi:[0,0,1]
	v_pk_fma_f32 v[88:89], v[88:89], s[16:17], v[14:15] op_sel_hi:[1,0,1] neg_lo:[0,0,1] neg_hi:[0,0,1]
	s_waitcnt lgkmcnt(3)
	v_pk_fma_f32 v[90:91], v[90:91], s[16:17], v[224:225] op_sel_hi:[1,0,1] neg_lo:[0,0,1] neg_hi:[0,0,1]
	v_pk_fma_f32 v[92:93], v[92:93], s[16:17], v[226:227] op_sel_hi:[1,0,1] neg_lo:[0,0,1] neg_hi:[0,0,1]
	s_waitcnt lgkmcnt(0)
	v_pk_fma_f32 v[94:95], v[94:95], s[16:17], v[232:233] op_sel_hi:[1,0,1] neg_lo:[0,0,1] neg_hi:[0,0,1]
	v_pk_fma_f32 v[96:97], v[96:97], s[16:17], v[234:235] op_sel_hi:[1,0,1] neg_lo:[0,0,1] neg_hi:[0,0,1]
	v_pk_fma_f32 v[98:99], v[98:99], s[16:17], v[4:5] op_sel_hi:[1,0,1] neg_lo:[0,0,1] neg_hi:[0,0,1]
	v_pk_fma_f32 v[100:101], v[100:101], s[16:17], v[6:7] op_sel_hi:[1,0,1] neg_lo:[0,0,1] neg_hi:[0,0,1]
	v_pk_fma_f32 v[102:103], v[102:103], s[16:17], v[220:221] op_sel_hi:[1,0,1] neg_lo:[0,0,1] neg_hi:[0,0,1]
	v_pk_fma_f32 v[104:105], v[104:105], s[16:17], v[222:223] op_sel_hi:[1,0,1] neg_lo:[0,0,1] neg_hi:[0,0,1]
	v_pk_fma_f32 v[106:107], v[106:107], s[16:17], v[228:229] op_sel_hi:[1,0,1] neg_lo:[0,0,1] neg_hi:[0,0,1]
	v_pk_fma_f32 v[108:109], v[108:109], s[16:17], v[230:231] op_sel_hi:[1,0,1] neg_lo:[0,0,1] neg_hi:[0,0,1]
	v_pk_fma_f32 v[110:111], v[110:111], s[16:17], v[236:237] op_sel_hi:[1,0,1] neg_lo:[0,0,1] neg_hi:[0,0,1]
	v_pk_fma_f32 v[112:113], v[112:113], s[16:17], v[238:239] op_sel_hi:[1,0,1] neg_lo:[0,0,1] neg_hi:[0,0,1]
	s_cbranch_scc1 .LBB0_557
	v_add_u32_e32 v2, s50, v178
	v_add_u32_e32 v4, 32, v2
	v_cmp_le_i32_e64 s[52:53], v4, v202
	v_add_u32_e32 v4, 33, v2
	v_cmp_le_i32_e64 s[54:55], v4, v202
	v_add_u32_e32 v4, 2, v2
	v_cmp_le_i32_e32 vcc, v2, v202
	v_cndmask_b32_e64 v99, v249, v99, s[54:55]
	v_cmp_le_i32_e64 s[54:55], v4, v202
	v_add_u32_e32 v4, 34, v2
	v_cmp_le_i32_e64 s[56:57], v4, v202
	v_add_u32_e32 v4, 3, v2
	v_cndmask_b32_e64 v98, v249, v98, s[52:53]
	v_cndmask_b32_e64 v100, v249, v100, s[56:57]
	v_cmp_le_i32_e64 s[56:57], v4, v202
	v_add_u32_e32 v4, 35, v2
	v_cmp_le_i32_e64 s[58:59], v4, v202
	v_add_u32_e32 v4, 8, v2
	v_cmp_lt_i32_e64 s[52:53], v2, v202
	v_cndmask_b32_e64 v101, v249, v101, s[58:59]
	v_cmp_le_i32_e64 s[58:59], v4, v202
	v_add_u32_e32 v4, 40, v2
	v_cmp_le_i32_e64 s[60:61], v4, v202
	v_add_u32_e32 v4, 9, v2
	s_nop 0
	v_cndmask_b32_e64 v102, v249, v102, s[60:61]
	v_cmp_le_i32_e64 s[60:61], v4, v202
	v_add_u32_e32 v4, 41, v2
	v_cmp_le_i32_e64 s[62:63], v4, v202
	v_add_u32_e32 v4, 10, v2
	s_nop 0
	v_cndmask_b32_e64 v103, v249, v103, s[62:63]
	v_cmp_le_i32_e64 s[62:63], v4, v202
	v_add_u32_e32 v4, 42, v2
	v_cmp_le_i32_e64 s[64:65], v4, v202
	v_add_u32_e32 v4, 11, v2
	s_nop 0
	v_cndmask_b32_e64 v104, v249, v104, s[64:65]
	v_cmp_le_i32_e64 s[64:65], v4, v202
	v_add_u32_e32 v4, 43, v2
	v_cmp_le_i32_e64 s[66:67], v4, v202
	v_add_u32_e32 v4, 16, v2
	s_nop 0
	v_cndmask_b32_e64 v105, v249, v105, s[66:67]
	v_cmp_le_i32_e64 s[66:67], v4, v202
	v_add_u32_e32 v4, 48, v2
	v_cmp_le_i32_e64 s[68:69], v4, v202
	v_add_u32_e32 v4, 17, v2
	s_nop 0
	v_cndmask_b32_e64 v106, v249, v106, s[68:69]
	v_cmp_le_i32_e64 s[68:69], v4, v202
	v_add_u32_e32 v4, 49, v2
	v_cmp_le_i32_e64 s[70:71], v4, v202
	v_add_u32_e32 v4, 18, v2
	s_nop 0
	v_cndmask_b32_e64 v107, v249, v107, s[70:71]
	v_cmp_le_i32_e64 s[70:71], v4, v202
	v_add_u32_e32 v4, 50, v2
	v_cmp_le_i32_e64 s[72:73], v4, v202
	v_add_u32_e32 v4, 19, v2
	s_nop 0
	v_cndmask_b32_e64 v108, v249, v108, s[72:73]
	v_cmp_le_i32_e64 s[72:73], v4, v202
	v_add_u32_e32 v4, 51, v2
	v_cmp_le_i32_e64 s[74:75], v4, v202
	v_add_u32_e32 v4, 24, v2
	s_nop 0
	v_cndmask_b32_e64 v109, v249, v109, s[74:75]
	v_cmp_le_i32_e64 s[74:75], v4, v202
	v_add_u32_e32 v4, 56, v2
	v_cmp_le_i32_e64 s[76:77], v4, v202
	v_add_u32_e32 v4, 25, v2
	s_nop 0
	v_cndmask_b32_e64 v110, v249, v110, s[76:77]
	v_cmp_le_i32_e64 s[76:77], v4, v202
	v_add_u32_e32 v4, 57, v2
	v_cmp_le_i32_e64 s[78:79], v4, v202
	v_add_u32_e32 v4, 26, v2
	s_nop 0
	v_cndmask_b32_e64 v111, v249, v111, s[78:79]
	v_cmp_le_i32_e64 s[78:79], v4, v202
	v_add_u32_e32 v4, 58, v2
	v_cmp_le_i32_e64 s[80:81], v4, v202
	v_add_u32_e32 v4, 27, v2
	v_add_u32_e32 v2, 59, v2
	v_cndmask_b32_e64 v112, v249, v112, s[80:81]
	v_cmp_le_i32_e64 s[80:81], v4, v202
	v_cmp_gt_i32_e64 s[84:85], v2, v202
	s_and_saveexec_b64 s[44:45], s[84:85]
	v_mov_b32_e32 v113, s21
	s_or_b64 exec, exec, s[44:45]
	v_cndmask_b32_e64 v83, v249, v83, s[52:53]
	v_cndmask_b32_e32 v82, v249, v82, vcc
	v_cndmask_b32_e64 v84, v249, v84, s[54:55]
	v_cndmask_b32_e64 v85, v249, v85, s[56:57]
	v_cndmask_b32_e64 v86, v249, v86, s[58:59]
	v_cndmask_b32_e64 v87, v249, v87, s[60:61]
	v_cndmask_b32_e64 v88, v249, v88, s[62:63]
	v_cndmask_b32_e64 v89, v249, v89, s[64:65]
	v_cndmask_b32_e64 v90, v249, v90, s[66:67]
	v_cndmask_b32_e64 v91, v249, v91, s[68:69]
	v_cndmask_b32_e64 v92, v249, v92, s[70:71]
	v_cndmask_b32_e64 v93, v249, v93, s[72:73]
	v_cndmask_b32_e64 v94, v249, v94, s[74:75]
	v_cndmask_b32_e64 v95, v249, v95, s[76:77]
	v_cndmask_b32_e64 v96, v249, v96, s[78:79]
	v_cndmask_b32_e64 v97, v249, v97, s[80:81]
.LBB0_557:
	s_andn2_b64 vcc, exec, s[6:7]
	s_cbranch_vccnz .LBB0_561
	v_max3_f32 v2, v82, v98, v99
	v_max3_f32 v4, v83, v100, v84
	v_max3_f32 v2, v2, v101, v85
	v_max3_f32 v4, v4, v102, v86
	v_max3_f32 v2, v2, v103, v87
	v_max3_f32 v4, v4, v104, v88
	v_max3_f32 v2, v2, v105, v89
	v_max3_f32 v4, v4, v106, v90
	v_max3_f32 v2, v2, v107, v91
	v_max3_f32 v4, v4, v108, v92
	v_max3_f32 v2, v2, v109, v93
	v_max3_f32 v4, v4, v110, v94
	v_max3_f32 v2, v2, v111, v95
	v_max3_f32 v4, v4, v112, v96
	v_max3_f32 v2, v2, v113, v97
	v_max_f32_e32 v2, v2, v4
	v_mov_b32_e32 v4, v2
	s_nop 1
	v_permlane32_swap_b32 v4, v2
	s_nop 1
	s_nop 0
	v_max3_f32 v203, v16, v4, v2
	v_sub_f32_e32 v2, v16, v203
	v_exp_f32_e32 v2, v2
	s_nop 0
	v_cmp_eq_f32_e32 vcc, 1.0, v2
	s_cmp_eq_u64 vcc, exec
	s_cbranch_scc1 .LBB0_560
	v_pk_mul_f32 v[80:81], v[80:81], v[2:3] op_sel_hi:[1,0]
	v_pk_mul_f32 v[78:79], v[78:79], v[2:3] op_sel_hi:[1,0]
	v_pk_mul_f32 v[76:77], v[76:77], v[2:3] op_sel_hi:[1,0]
	v_pk_mul_f32 v[74:75], v[74:75], v[2:3] op_sel_hi:[1,0]
	v_pk_mul_f32 v[72:73], v[72:73], v[2:3] op_sel_hi:[1,0]
	v_pk_mul_f32 v[70:71], v[70:71], v[2:3] op_sel_hi:[1,0]
	v_pk_mul_f32 v[68:69], v[68:69], v[2:3] op_sel_hi:[1,0]
	v_pk_mul_f32 v[66:67], v[66:67], v[2:3] op_sel_hi:[1,0]
	v_pk_mul_f32 v[64:65], v[64:65], v[2:3] op_sel_hi:[1,0]
	v_pk_mul_f32 v[62:63], v[62:63], v[2:3] op_sel_hi:[1,0]
	v_pk_mul_f32 v[60:61], v[60:61], v[2:3] op_sel_hi:[1,0]
	v_pk_mul_f32 v[58:59], v[58:59], v[2:3] op_sel_hi:[1,0]
	v_pk_mul_f32 v[56:57], v[56:57], v[2:3] op_sel_hi:[1,0]
	v_pk_mul_f32 v[54:55], v[54:55], v[2:3] op_sel_hi:[1,0]
	v_pk_mul_f32 v[52:53], v[52:53], v[2:3] op_sel_hi:[1,0]
	v_pk_mul_f32 v[50:51], v[50:51], v[2:3] op_sel_hi:[1,0]
	v_pk_mul_f32 v[48:49], v[48:49], v[2:3] op_sel_hi:[1,0]
	v_pk_mul_f32 v[46:47], v[46:47], v[2:3] op_sel_hi:[1,0]
	v_pk_mul_f32 v[44:45], v[44:45], v[2:3] op_sel_hi:[1,0]
	v_pk_mul_f32 v[42:43], v[42:43], v[2:3] op_sel_hi:[1,0]
	v_pk_mul_f32 v[40:41], v[40:41], v[2:3] op_sel_hi:[1,0]
	v_pk_mul_f32 v[38:39], v[38:39], v[2:3] op_sel_hi:[1,0]
	v_pk_mul_f32 v[36:37], v[36:37], v[2:3] op_sel_hi:[1,0]
	v_pk_mul_f32 v[34:35], v[34:35], v[2:3] op_sel_hi:[1,0]
	v_pk_mul_f32 v[32:33], v[32:33], v[2:3] op_sel_hi:[1,0]
	v_pk_mul_f32 v[30:31], v[30:31], v[2:3] op_sel_hi:[1,0]
	v_pk_mul_f32 v[28:29], v[28:29], v[2:3] op_sel_hi:[1,0]
	v_pk_mul_f32 v[26:27], v[26:27], v[2:3] op_sel_hi:[1,0]
	v_pk_mul_f32 v[24:25], v[24:25], v[2:3] op_sel_hi:[1,0]
	v_pk_mul_f32 v[22:23], v[22:23], v[2:3] op_sel_hi:[1,0]
	v_pk_mul_f32 v[20:21], v[20:21], v[2:3] op_sel_hi:[1,0]
	v_pk_mul_f32 v[18:19], v[18:19], v[2:3] op_sel_hi:[1,0]

.LBB0_565:
	s_sub_i32 s50, s50, 64
	s_add_i32 s49, s49, 1
	s_cmpk_eq_i32 s50, 0xffc0
	v_add_u32_e32 v183, 0xffffff00, v183
	s_waitcnt lgkmcnt(0)
	s_barrier
	s_cbranch_scc0 .LBB0_546
	s_and_b64 s[34:35], s[0:1], s[42:43]
	s_and_b64 vcc, exec, s[34:35]
	s_cbranch_vccz .LBB0_531
	v_max3_f32 v2, v82, v98, v99
	v_max3_f32 v4, v83, v100, v84
	v_max3_f32 v2, v2, v101, v85
	v_max3_f32 v4, v4, v102, v86
	v_max3_f32 v2, v2, v103, v87
	v_max3_f32 v4, v4, v104, v88
	v_max3_f32 v2, v2, v105, v89
	v_max3_f32 v4, v4, v106, v90
	v_max3_f32 v2, v2, v107, v91
	v_max3_f32 v4, v4, v108, v92
	v_max3_f32 v2, v2, v109, v93
	v_max3_f32 v4, v4, v110, v94
	v_max3_f32 v2, v2, v111, v95
	v_max3_f32 v4, v4, v112, v96
	v_max3_f32 v2, v2, v113, v97
	v_max_f32_e32 v2, v2, v4
	v_mov_b32_e32 v4, v2
	s_nop 1
	v_permlane32_swap_b32 v4, v2
	s_nop 1
	s_nop 0
	v_max3_f32 v4, v203, v4, v2
	v_sub_f32_e32 v2, v203, v4
	v_exp_f32_e32 v2, v2
	s_nop 0
	v_cmp_eq_f32_e32 vcc, 1.0, v2
	s_cmp_eq_u64 vcc, exec
	s_cbranch_scc1 .LBB0_530
	v_pk_mul_f32 v[80:81], v[80:81], v[2:3] op_sel_hi:[1,0]
	v_pk_mul_f32 v[78:79], v[78:79], v[2:3] op_sel_hi:[1,0]
	v_pk_mul_f32 v[76:77], v[76:77], v[2:3] op_sel_hi:[1,0]
	v_pk_mul_f32 v[74:75], v[74:75], v[2:3] op_sel_hi:[1,0]
	v_pk_mul_f32 v[72:73], v[72:73], v[2:3] op_sel_hi:[1,0]
	v_pk_mul_f32 v[70:71], v[70:71], v[2:3] op_sel_hi:[1,0]
	v_pk_mul_f32 v[68:69], v[68:69], v[2:3] op_sel_hi:[1,0]
	v_pk_mul_f32 v[66:67], v[66:67], v[2:3] op_sel_hi:[1,0]
	v_pk_mul_f32 v[64:65], v[64:65], v[2:3] op_sel_hi:[1,0]
	v_pk_mul_f32 v[62:63], v[62:63], v[2:3] op_sel_hi:[1,0]
	v_pk_mul_f32 v[60:61], v[60:61], v[2:3] op_sel_hi:[1,0]
	v_pk_mul_f32 v[58:59], v[58:59], v[2:3] op_sel_hi:[1,0]
	v_pk_mul_f32 v[56:57], v[56:57], v[2:3] op_sel_hi:[1,0]
	v_pk_mul_f32 v[54:55], v[54:55], v[2:3] op_sel_hi:[1,0]
	v_pk_mul_f32 v[52:53], v[52:53], v[2:3] op_sel_hi:[1,0]
	v_pk_mul_f32 v[50:51], v[50:51], v[2:3] op_sel_hi:[1,0]
	v_pk_mul_f32 v[48:49], v[48:49], v[2:3] op_sel_hi:[1,0]
	v_pk_mul_f32 v[46:47], v[46:47], v[2:3] op_sel_hi:[1,0]
	v_pk_mul_f32 v[44:45], v[44:45], v[2:3] op_sel_hi:[1,0]
	v_pk_mul_f32 v[42:43], v[42:43], v[2:3] op_sel_hi:[1,0]
	v_pk_mul_f32 v[40:41], v[40:41], v[2:3] op_sel_hi:[1,0]
	v_pk_mul_f32 v[38:39], v[38:39], v[2:3] op_sel_hi:[1,0]
	v_pk_mul_f32 v[36:37], v[36:37], v[2:3] op_sel_hi:[1,0]
	v_pk_mul_f32 v[34:35], v[34:35], v[2:3] op_sel_hi:[1,0]
	v_pk_mul_f32 v[32:33], v[32:33], v[2:3] op_sel_hi:[1,0]
	v_pk_mul_f32 v[30:31], v[30:31], v[2:3] op_sel_hi:[1,0]
	v_pk_mul_f32 v[28:29], v[28:29], v[2:3] op_sel_hi:[1,0]
	v_pk_mul_f32 v[26:27], v[26:27], v[2:3] op_sel_hi:[1,0]
	v_pk_mul_f32 v[24:25], v[24:25], v[2:3] op_sel_hi:[1,0]
	v_pk_mul_f32 v[22:23], v[22:23], v[2:3] op_sel_hi:[1,0]
	v_pk_mul_f32 v[20:21], v[20:21], v[2:3] op_sel_hi:[1,0]
	v_pk_mul_f32 v[18:19], v[18:19], v[2:3] op_sel_hi:[1,0]
	s_branch .LBB0_530
